# in-proj epilogue: per-unit ssq table prefetched into LDS by LDS-DMA (same scheme as FFN-up epilogue)
# speedup vs baseline: 1.0236x; 1.0041x over previous
; #define PG8_STAGE(bufoff, gbase, voff) do { _Pragma("unroll") for (int _i = 0; _i < 2; ++_i) \
;         __builtin_amdgcn_global_load_lds((const unsigned*)((const char*)(gbase) + (voff)[_i]), (LAS unsigned*)(lds + (bufoff) + ldsw + _i * 8192), 16, 0, 0); } while (0)
; #define PG8_LDA(dst, b, h) do { _Pragma("unroll") for (int m = 0; m < 4; ++m) _Pragma("unroll") for (int k = 0; k < 2; ++k) dst[m][k] = *(const LAS bf16x8*)(lds + PG8_SA(b, h) + aoff + m * 2048 + k * 1024); } while (0)
; #define PG8_LDB(dst, b, h) do { _Pragma("unroll") for (int n = 0; n < 2; ++n) _Pragma("unroll") for (int k = 0; k < 2; ++k) dst[n][k] = *(const LAS bf16x8*)(lds + PG8_SB(b, h) + boff + n * 2048 + k * 1024); } while (0)
; #define PG8_MMA(ai, bj, At, Bt) do { __builtin_amdgcn_s_setprio(1); _Pragma("unroll") for (int m = 0; m < 4; ++m) _Pragma("unroll") for (int n = 0; n < 2; ++n) _Pragma("unroll") for (int k = 0; k < 2; ++k) \
;         acc[ai][bj][m][n] = __builtin_amdgcn_mfma_f32_16x16x32_bf16(Bt[n][k], At[m][k], acc[ai][bj][m][n], 0, 0, 0); __builtin_amdgcn_s_setprio(0); } while (0)
; template <class Epi, class Sched, bool APERM = false, bool HALFN = false>
; __device__ __forceinline__ void gemm_phase(LAS unsigned char* lds, const int tid_in, const int K, const Sched& S, const Epi& E) {
;     ...
;         const bool has_next = S.next(ui + 1, nxt);
;         const char* nA = has_next ? nxt.A : cA; const char* nB = has_next ? nxt.B : cB;
;         for (int t = 0; t < nt; t += 2) {
;             const bool last = (t == nt - 2);
;             const char* a1 = cA + (size_t)(t + 1) * kstep;
;             const char* a2 = last ? nA : cA + (size_t)(t + 2) * kstep; const char* b2 = last ? nB : cB + (size_t)(t + 2) * kstep;
;             const char* a3 = a2 + kstep; const char* b3 = b2 + kstep;
;             PG8_LDB(B0, 0, 0); PG8_LDB(B1, 0, 1); PG8_SCHED; PG8_LDA(At, 0, 0); PG8_STAGE(PG8_SA(1, 1), a1 + hstepA, voffA);
;             PG8_WAIT_V(8); PG8_WAIT_L(0); PG8_BAR; PG8_MMA(0, 0, At, B0); if constexpr (!HALFN) PG8_MMA(0, 1, At, B1); PG8_BAR; PG8_SCHED;
;     ...
; #pragma unroll
;         for (int a = 0; a < 2; ++a)
; #pragma unroll
;             for (int b = 0; b < 2; ++b)
; #pragma unroll
;                 for (int m = 0; m < 4; ++m)
; #pragma unroll
;                     for (int n = 0; n < 2; ++n) acc[a][b][m][n] = (f32x4){0.f, 0.f, 0.f, 0.f};
;         cur = nxt; cA = nA; cB = nB; ++ui;
.LBB0_345:
	s_and_b64 s[16:17], s[14:15], exec
	s_cselect_b32 s19, s11, s1
	s_cselect_b32 s20, s10, s0
	s_cselect_b32 s21, s13, s5
	s_cselect_b32 s22, s12, s4
	s_add_u32 s23, s4, 0x100
	s_addc_u32 s24, s5, 0
	s_add_u32 s0, s0, 0x80080
	v_mov_b32_e32 v0, 0
	s_addc_u32 s1, s1, 0
	s_mov_b32 s25, -2
	v_mov_b32_e32 v1, v0
	v_mov_b32_e32 v2, v0
	v_mov_b32_e32 v3, v0
	v_mov_b32_e32 v4, v0
	v_mov_b32_e32 v5, v0
	v_mov_b32_e32 v6, v0
	v_mov_b32_e32 v7, v0
	v_mov_b32_e32 v16, v0
	v_mov_b32_e32 v17, v0
	v_mov_b32_e32 v18, v0
	v_mov_b32_e32 v19, v0
	v_mov_b32_e32 v20, v0
	v_mov_b32_e32 v21, v0
	v_mov_b32_e32 v22, v0
	v_mov_b32_e32 v23, v0
	v_mov_b32_e32 v32, v0
	v_mov_b32_e32 v33, v0
	v_mov_b32_e32 v34, v0
	v_mov_b32_e32 v35, v0
	v_mov_b32_e32 v36, v0
	v_mov_b32_e32 v37, v0
	v_mov_b32_e32 v38, v0
	v_mov_b32_e32 v39, v0
	v_mov_b32_e32 v48, v0
	v_mov_b32_e32 v49, v0
	v_mov_b32_e32 v50, v0
	v_mov_b32_e32 v51, v0
	v_mov_b32_e32 v52, v0
	v_mov_b32_e32 v53, v0
	v_mov_b32_e32 v54, v0
	v_mov_b32_e32 v55, v0
	v_mov_b32_e32 v8, v0
	v_mov_b32_e32 v9, v0
	v_mov_b32_e32 v10, v0
	v_mov_b32_e32 v11, v0
	v_mov_b32_e32 v12, v0
	v_mov_b32_e32 v13, v0
	v_mov_b32_e32 v14, v0
	v_mov_b32_e32 v15, v0
	v_mov_b32_e32 v24, v0
	v_mov_b32_e32 v25, v0
	v_mov_b32_e32 v26, v0
	v_mov_b32_e32 v27, v0
	v_mov_b32_e32 v28, v0
	v_mov_b32_e32 v29, v0
	v_mov_b32_e32 v30, v0
	v_mov_b32_e32 v31, v0
	v_mov_b32_e32 v40, v0
	v_mov_b32_e32 v41, v0
	v_mov_b32_e32 v42, v0
	v_mov_b32_e32 v43, v0
	v_mov_b32_e32 v44, v0
	v_mov_b32_e32 v45, v0
	v_mov_b32_e32 v46, v0
	v_mov_b32_e32 v47, v0
	v_mov_b32_e32 v56, v0
	v_mov_b32_e32 v57, v0
	v_mov_b32_e32 v58, v0
	v_mov_b32_e32 v59, v0
	v_mov_b32_e32 v60, v0
	v_mov_b32_e32 v61, v0
	v_mov_b32_e32 v62, v0
	v_mov_b32_e32 v63, v0
	v_mov_b32_e32 v64, v0
	v_mov_b32_e32 v65, v0
	v_mov_b32_e32 v66, v0
	v_mov_b32_e32 v67, v0
	v_mov_b32_e32 v68, v0
	v_mov_b32_e32 v69, v0
	v_mov_b32_e32 v70, v0
	v_mov_b32_e32 v71, v0
	v_mov_b32_e32 v80, v0
	v_mov_b32_e32 v81, v0
	v_mov_b32_e32 v82, v0
	v_mov_b32_e32 v83, v0
	v_mov_b32_e32 v84, v0
	v_mov_b32_e32 v85, v0
	v_mov_b32_e32 v86, v0
	v_mov_b32_e32 v87, v0
	v_mov_b32_e32 v96, v0
	v_mov_b32_e32 v97, v0
	v_mov_b32_e32 v98, v0
	v_mov_b32_e32 v99, v0
	v_mov_b32_e32 v100, v0
	v_mov_b32_e32 v101, v0
	v_mov_b32_e32 v102, v0
	v_mov_b32_e32 v103, v0
	v_mov_b32_e32 v112, v0
	v_mov_b32_e32 v113, v0
	v_mov_b32_e32 v114, v0
	v_mov_b32_e32 v115, v0
	v_mov_b32_e32 v116, v0
	v_mov_b32_e32 v117, v0
	v_mov_b32_e32 v118, v0
	v_mov_b32_e32 v119, v0
	v_mov_b32_e32 v72, v0
	v_mov_b32_e32 v73, v0
	v_mov_b32_e32 v74, v0
	v_mov_b32_e32 v75, v0
	v_mov_b32_e32 v76, v0
	v_mov_b32_e32 v77, v0
	v_mov_b32_e32 v78, v0
	v_mov_b32_e32 v79, v0
	v_mov_b32_e32 v88, v0
	v_mov_b32_e32 v89, v0
	v_mov_b32_e32 v90, v0
	v_mov_b32_e32 v91, v0
	v_mov_b32_e32 v92, v0
	v_mov_b32_e32 v93, v0
	v_mov_b32_e32 v94, v0
	v_mov_b32_e32 v95, v0
	v_mov_b32_e32 v104, v0
	v_mov_b32_e32 v105, v0
	v_mov_b32_e32 v106, v0
	v_mov_b32_e32 v107, v0
	v_mov_b32_e32 v108, v0
	v_mov_b32_e32 v109, v0
	v_mov_b32_e32 v110, v0
	v_mov_b32_e32 v111, v0
	v_mov_b32_e32 v120, v0
	v_mov_b32_e32 v121, v0
	v_mov_b32_e32 v122, v0
	v_mov_b32_e32 v123, v0
	v_mov_b32_e32 v124, v0
	v_mov_b32_e32 v125, v0
	v_mov_b32_e32 v126, v0
	v_mov_b32_e32 v127, v0
	v_readfirstlane_b32 s16, v234
	s_mul_i32 s17, s18, s28
	s_add_i32 s17, s17, s27
	s_lshr_b32 s16, s16, 6
	s_cmp_gt_u32 s16, 1
	s_cbranch_scc1 .Lpfb_done
	s_cmpk_gt_u32 s17, 0x25f
	s_cbranch_scc1 .Lpfb_done
	s_cmpk_gt_u32 s17, 0x1bf
	s_cselect_b32 s44, s4, s0
	s_sub_u32 s44, s44, s29
	s_lshr_b32 s44, s44, 20
	s_lshl_b32 s44, s44, 11
	s_lshl_b32 s72, s16, 10
	s_add_i32 s44, s44, s72
	s_add_u32 s44, s81, s44
	s_addc_u32 s45, s86, 0
	s_and_b32 s17, s18, 1
	s_lshl_b32 s17, s17, 11
	s_add_i32 s17, s17, s72
	s_add_i32 s17, s17, 0x20000
	v_lshlrev_b32_e32 v236, 4, v235
	v_mov_b32_e32 v237, 0
	v_lshl_add_u64 v[236:237], s[44:45], 0, v[236:237]
	s_mov_b32 m0, s17
	s_nop 0
	global_load_lds_dwordx4 v[236:237], off
.Lpfb_done:
.LBB0_346:
	s_add_u32 s4, s0, 0xfff80080
	s_addc_u32 s5, s1, -1
	s_add_i32 s44, 0, 0x10000
	s_cmp_eq_u32 s25, 28
	s_cselect_b32 s17, s19, s5
	s_cselect_b32 s16, s20, s4
	s_cselect_b32 s5, s21, s24
	s_cselect_b32 s4, s22, s23
	s_add_i32 s52, 0, 0x14000
	v_add_u32_e32 v180, s44, v139
	v_add_u32_e32 v196, s52, v139
	ds_read_b128 v[168:171], v180
	ds_read_b128 v[172:175], v180 offset:1024
	ds_read_b128 v[176:179], v180 offset:2048
	ds_read_b128 v[180:183], v180 offset:3072
	ds_read_b128 v[184:187], v196
	ds_read_b128 v[188:191], v196 offset:1024
	ds_read_b128 v[192:195], v196 offset:2048
	ds_read_b128 v[196:199], v196 offset:3072
	v_lshl_add_u64 v[232:233], s[0:1], 0, v[166:167]
	s_add_i32 m0, s38, 0xc000
	ds_read_b128 v[204:207], v141
	ds_read_b128 v[208:211], v141 offset:1024
	ds_read_b128 v[212:215], v141 offset:2048
	ds_read_b128 v[216:219], v141 offset:3072
	ds_read_b128 v[220:223], v141 offset:4096
	ds_read_b128 v[224:227], v141 offset:5120
	ds_read_b128 v[228:231], v141 offset:6144
	ds_read_b128 v[244:247], v141 offset:7168
	global_load_lds_dwordx4 v[232:233], off
	v_lshl_add_u64 v[232:233], s[0:1], 0, v[164:165]
	s_add_i32 m0, s38, 0xe000
	s_nop 0
	global_load_lds_dwordx4 v[232:233], off
	s_waitcnt vmcnt(8)
	s_waitcnt lgkmcnt(0)
	s_barrier
; #define PG8_STAGE(bufoff, gbase, voff) do { _Pragma("unroll") for (int _i = 0; _i < 2; ++_i) \
;         __builtin_amdgcn_global_load_lds((const unsigned*)((const char*)(gbase) + (voff)[_i]), (LAS unsigned*)(lds + (bufoff) + ldsw + _i * 8192), 16, 0, 0); } while (0)
; #define PG8_LDA(dst, b, h) do { _Pragma("unroll") for (int m = 0; m < 4; ++m) _Pragma("unroll") for (int k = 0; k < 2; ++k) dst[m][k] = *(const LAS bf16x8*)(lds + PG8_SA(b, h) + aoff + m * 2048 + k * 1024); } while (0)
; #define PG8_MMA(ai, bj, At, Bt) do { __builtin_amdgcn_s_setprio(1); _Pragma("unroll") for (int m = 0; m < 4; ++m) _Pragma("unroll") for (int n = 0; n < 2; ++n) _Pragma("unroll") for (int k = 0; k < 2; ++k) \
;         acc[ai][bj][m][n] = __builtin_amdgcn_mfma_f32_16x16x32_bf16(Bt[n][k], At[m][k], acc[ai][bj][m][n], 0, 0, 0); __builtin_amdgcn_s_setprio(0); } while (0)
; #define PG8_WAIT_V(n) asm volatile("s_waitcnt vmcnt(" #n ")" ::: "memory")
; #define PG8_WAIT_L(n) asm volatile("s_waitcnt lgkmcnt(" #n ")" ::: "memory")
; #define PG8_BAR __builtin_amdgcn_s_barrier()
; #define PG8_SCHED __builtin_amdgcn_sched_barrier(0)
; template <class Epi, class Sched, bool APERM = false, bool HALFN = false>
; __device__ __forceinline__ void gemm_phase(LAS unsigned char* lds, const int tid_in, const int K, const Sched& S, const Epi& E) {
;     ...
;             PG8_WAIT_V(8); PG8_WAIT_L(0); PG8_BAR; PG8_MMA(0, 0, At, B0); if constexpr (!HALFN) PG8_MMA(0, 1, At, B1); PG8_BAR; PG8_SCHED;
;             PG8_LDA(At, 0, 1); PG8_STAGE(PG8_SB(0, 0), b2, voffB); PG8_STAGE(PG8_SB(0, 1), b2 + hstep, voffB); PG8_STAGE(PG8_SA(0, 0), a2, voffA);
;             PG8_WAIT_V(8); PG8_WAIT_L(0); PG8_BAR; PG8_MMA(1, 0, At, B0); if constexpr (!HALFN) PG8_MMA(1, 1, At, B1); PG8_BAR; PG8_SCHED;
	s_setprio 1
	s_waitcnt lgkmcnt(0)
	v_mfma_f32_16x16x32_bf16 v[124:127], v[168:171], v[204:207], v[124:127]
	v_mfma_f32_16x16x32_bf16 v[120:123], v[176:179], v[204:207], v[120:123]
	v_mfma_f32_16x16x32_bf16 v[108:111], v[168:171], v[212:215], v[108:111]
	v_mfma_f32_16x16x32_bf16 v[104:107], v[176:179], v[212:215], v[104:107]
	v_mfma_f32_16x16x32_bf16 v[92:95], v[168:171], v[220:223], v[92:95]
	v_mfma_f32_16x16x32_bf16 v[88:91], v[176:179], v[220:223], v[88:91]
	v_mfma_f32_16x16x32_bf16 v[76:79], v[168:171], v[228:231], v[76:79]
	v_mfma_f32_16x16x32_bf16 v[72:75], v[176:179], v[228:231], v[72:75]
	v_mfma_f32_16x16x32_bf16 v[124:127], v[172:175], v[208:211], v[124:127]
	v_mfma_f32_16x16x32_bf16 v[120:123], v[180:183], v[208:211], v[120:123]
	v_mfma_f32_16x16x32_bf16 v[108:111], v[172:175], v[216:219], v[108:111]
	v_mfma_f32_16x16x32_bf16 v[104:107], v[180:183], v[216:219], v[104:107]
	v_mfma_f32_16x16x32_bf16 v[92:95], v[172:175], v[224:227], v[92:95]
	v_mfma_f32_16x16x32_bf16 v[88:91], v[180:183], v[224:227], v[88:91]
	v_mfma_f32_16x16x32_bf16 v[76:79], v[172:175], v[244:247], v[76:79]
	v_mfma_f32_16x16x32_bf16 v[72:75], v[180:183], v[244:247], v[72:75]
	s_setprio 0
	s_setprio 1
	v_mfma_f32_16x16x32_bf16 v[116:119], v[184:187], v[204:207], v[116:119]
	v_mfma_f32_16x16x32_bf16 v[112:115], v[192:195], v[204:207], v[112:115]
	v_mfma_f32_16x16x32_bf16 v[100:103], v[184:187], v[212:215], v[100:103]
	v_mfma_f32_16x16x32_bf16 v[96:99], v[192:195], v[212:215], v[96:99]
	v_mfma_f32_16x16x32_bf16 v[84:87], v[184:187], v[220:223], v[84:87]
	v_mfma_f32_16x16x32_bf16 v[80:83], v[192:195], v[220:223], v[80:83]
	v_mfma_f32_16x16x32_bf16 v[68:71], v[184:187], v[228:231], v[68:71]
	v_mfma_f32_16x16x32_bf16 v[64:67], v[192:195], v[228:231], v[64:67]
	v_mfma_f32_16x16x32_bf16 v[116:119], v[188:191], v[208:211], v[116:119]
	v_mfma_f32_16x16x32_bf16 v[112:115], v[196:199], v[208:211], v[112:115]
	v_mfma_f32_16x16x32_bf16 v[100:103], v[188:191], v[216:219], v[100:103]
	v_mfma_f32_16x16x32_bf16 v[96:99], v[196:199], v[216:219], v[96:99]
	v_mfma_f32_16x16x32_bf16 v[84:87], v[188:191], v[224:227], v[84:87]
	v_mfma_f32_16x16x32_bf16 v[80:83], v[196:199], v[224:227], v[80:83]
	v_mfma_f32_16x16x32_bf16 v[68:71], v[188:191], v[244:247], v[68:71]
	v_mfma_f32_16x16x32_bf16 v[64:67], v[196:199], v[244:247], v[64:67]
	s_setprio 0
	s_barrier
	s_add_i32 s44, s44, s35
	v_lshl_add_u64 v[232:233], s[4:5], 0, v[130:131]
	s_mov_b32 m0, s44
	ds_read_b128 v[204:207], v141 offset:16384
	ds_read_b128 v[208:211], v141 offset:17408
	ds_read_b128 v[212:215], v141 offset:18432
	ds_read_b128 v[216:219], v141 offset:19456
	ds_read_b128 v[220:223], v141 offset:20480
	ds_read_b128 v[224:227], v141 offset:21504
	ds_read_b128 v[228:231], v141 offset:22528
	ds_read_b128 v[244:247], v141 offset:23552
	global_load_lds_dwordx4 v[232:233], off
	s_add_i32 m0, s44, 0x2000
	s_add_u32 s44, s4, 0x80000
	v_lshl_add_u64 v[248:249], s[4:5], 0, v[134:135]
	s_addc_u32 s45, s5, 0
	s_add_i32 s52, s52, s35
	global_load_lds_dwordx4 v[248:249], off
	v_lshl_add_u64 v[250:251], s[44:45], 0, v[130:131]
	s_mov_b32 m0, s52
	v_lshl_add_u64 v[252:253], s[16:17], 0, v[132:133]
	global_load_lds_dwordx4 v[250:251], off
	v_lshl_add_u64 v[250:251], s[44:45], 0, v[134:135]
	s_add_i32 m0, s52, 0x2000
	s_nop 0
	global_load_lds_dwordx4 v[250:251], off
	v_lshl_add_u64 v[250:251], s[16:17], 0, v[128:129]
	s_mov_b32 m0, s38
	s_nop 0
	global_load_lds_dwordx4 v[250:251], off
	s_mov_b32 m0, s39
	s_nop 0
	global_load_lds_dwordx4 v[252:253], off
	s_waitcnt vmcnt(8)
	s_waitcnt lgkmcnt(0)
	s_barrier
	s_setprio 1
	s_waitcnt lgkmcnt(0)
	v_mfma_f32_16x16x32_bf16 v[60:63], v[168:171], v[204:207], v[60:63]
	v_mfma_f32_16x16x32_bf16 v[56:59], v[176:179], v[204:207], v[56:59]
	v_mfma_f32_16x16x32_bf16 v[44:47], v[168:171], v[212:215], v[44:47]
	v_mfma_f32_16x16x32_bf16 v[40:43], v[176:179], v[212:215], v[40:43]
	v_mfma_f32_16x16x32_bf16 v[28:31], v[168:171], v[220:223], v[28:31]
	v_mfma_f32_16x16x32_bf16 v[24:27], v[176:179], v[220:223], v[24:27]
	v_mfma_f32_16x16x32_bf16 v[12:15], v[168:171], v[228:231], v[12:15]
	v_mfma_f32_16x16x32_bf16 v[8:11], v[176:179], v[228:231], v[8:11]
	v_mfma_f32_16x16x32_bf16 v[60:63], v[172:175], v[208:211], v[60:63]
	v_mfma_f32_16x16x32_bf16 v[56:59], v[180:183], v[208:211], v[56:59]
	v_mfma_f32_16x16x32_bf16 v[44:47], v[172:175], v[216:219], v[44:47]
	v_mfma_f32_16x16x32_bf16 v[40:43], v[180:183], v[216:219], v[40:43]
	v_mfma_f32_16x16x32_bf16 v[28:31], v[172:175], v[224:227], v[28:31]
	v_mfma_f32_16x16x32_bf16 v[24:27], v[180:183], v[224:227], v[24:27]
	v_mfma_f32_16x16x32_bf16 v[12:15], v[172:175], v[244:247], v[12:15]
	v_mfma_f32_16x16x32_bf16 v[8:11], v[180:183], v[244:247], v[8:11]
	s_setprio 0
	s_setprio 1
	v_mfma_f32_16x16x32_bf16 v[52:55], v[184:187], v[204:207], v[52:55]
	v_mfma_f32_16x16x32_bf16 v[48:51], v[192:195], v[204:207], v[48:51]
	v_mfma_f32_16x16x32_bf16 v[36:39], v[184:187], v[212:215], v[36:39]
	v_mfma_f32_16x16x32_bf16 v[32:35], v[192:195], v[212:215], v[32:35]
	v_mfma_f32_16x16x32_bf16 v[20:23], v[184:187], v[220:223], v[20:23]
	v_mfma_f32_16x16x32_bf16 v[16:19], v[192:195], v[220:223], v[16:19]
	v_mfma_f32_16x16x32_bf16 v[4:7], v[184:187], v[228:231], v[4:7]
	v_mfma_f32_16x16x32_bf16 v[0:3], v[192:195], v[228:231], v[0:3]
	v_mfma_f32_16x16x32_bf16 v[52:55], v[188:191], v[208:211], v[52:55]
	v_mfma_f32_16x16x32_bf16 v[48:51], v[196:199], v[208:211], v[48:51]
	v_mfma_f32_16x16x32_bf16 v[36:39], v[188:191], v[216:219], v[36:39]
	v_mfma_f32_16x16x32_bf16 v[32:35], v[196:199], v[216:219], v[32:35]
	v_mfma_f32_16x16x32_bf16 v[20:23], v[188:191], v[224:227], v[20:23]
	v_mfma_f32_16x16x32_bf16 v[16:19], v[196:199], v[224:227], v[16:19]
	v_mfma_f32_16x16x32_bf16 v[4:7], v[188:191], v[244:247], v[4:7]
	v_mfma_f32_16x16x32_bf16 v[0:3], v[196:199], v[244:247], v[0:3]
	s_setprio 0
	s_barrier
; #define PG8_STAGE(bufoff, gbase, voff) do { _Pragma("unroll") for (int _i = 0; _i < 2; ++_i) \
;         __builtin_amdgcn_global_load_lds((const unsigned*)((const char*)(gbase) + (voff)[_i]), (LAS unsigned*)(lds + (bufoff) + ldsw + _i * 8192), 16, 0, 0); } while (0)
; #define PG8_LDA(dst, b, h) do { _Pragma("unroll") for (int m = 0; m < 4; ++m) _Pragma("unroll") for (int k = 0; k < 2; ++k) dst[m][k] = *(const LAS bf16x8*)(lds + PG8_SA(b, h) + aoff + m * 2048 + k * 1024); } while (0)
; #define PG8_LDB(dst, b, h) do { _Pragma("unroll") for (int n = 0; n < 2; ++n) _Pragma("unroll") for (int k = 0; k < 2; ++k) dst[n][k] = *(const LAS bf16x8*)(lds + PG8_SB(b, h) + boff + n * 2048 + k * 1024); } while (0)
; #define PG8_MMA(ai, bj, At, Bt) do { __builtin_amdgcn_s_setprio(1); _Pragma("unroll") for (int m = 0; m < 4; ++m) _Pragma("unroll") for (int n = 0; n < 2; ++n) _Pragma("unroll") for (int k = 0; k < 2; ++k) \
;         acc[ai][bj][m][n] = __builtin_amdgcn_mfma_f32_16x16x32_bf16(Bt[n][k], At[m][k], acc[ai][bj][m][n], 0, 0, 0); __builtin_amdgcn_s_setprio(0); } while (0)
; #define PG8_WAIT_V(n) asm volatile("s_waitcnt vmcnt(" #n ")" ::: "memory")
; #define PG8_WAIT_L(n) asm volatile("s_waitcnt lgkmcnt(" #n ")" ::: "memory")
; #define PG8_BAR __builtin_amdgcn_s_barrier()
; #define PG8_SCHED __builtin_amdgcn_sched_barrier(0)
; template <class Epi, class Sched, bool APERM = false, bool HALFN = false>
; __device__ __forceinline__ void gemm_phase(LAS unsigned char* lds, const int tid_in, const int K, const Sched& S, const Epi& E) {
;     ...
;             PG8_LDB(B0, 1, 0); PG8_LDB(B1, 1, 1); PG8_SCHED; PG8_LDA(At, 1, 0); PG8_STAGE(PG8_SA(0, 1), a2 + hstepA, voffA);
;             PG8_WAIT_V(8); PG8_WAIT_L(0); PG8_BAR; PG8_MMA(0, 0, At, B0); if constexpr (!HALFN) PG8_MMA(0, 1, At, B1); PG8_BAR; PG8_SCHED;
	s_add_i32 s44, 0, 0x18000
	s_add_i32 s45, 0, 0x1c000
	v_add_u32_e32 v180, s44, v139
	v_add_u32_e32 v196, s45, v139
	ds_read_b128 v[168:171], v180
	ds_read_b128 v[172:175], v180 offset:1024
	ds_read_b128 v[176:179], v180 offset:2048
	ds_read_b128 v[180:183], v180 offset:3072
	ds_read_b128 v[184:187], v196
	ds_read_b128 v[188:191], v196 offset:1024
	ds_read_b128 v[192:195], v196 offset:2048
	ds_read_b128 v[196:199], v196 offset:3072
	s_add_u32 s16, s16, 0x80000
	s_addc_u32 s17, s17, 0
	s_mov_b32 m0, s57
	v_lshl_add_u64 v[236:237], s[16:17], 0, v[128:129]
	ds_read_b128 v[204:207], v141 offset:32768
	ds_read_b128 v[208:211], v141 offset:33792
	ds_read_b128 v[212:215], v141 offset:34816
	ds_read_b128 v[216:219], v141 offset:35840
	ds_read_b128 v[220:223], v141 offset:36864
	ds_read_b128 v[224:227], v141 offset:37888
	ds_read_b128 v[228:231], v141 offset:38912
	ds_read_b128 v[244:247], v141 offset:39936
	global_load_lds_dwordx4 v[236:237], off
	v_lshl_add_u64 v[236:237], s[16:17], 0, v[132:133]
	s_mov_b32 m0, s70
	s_nop 0
	global_load_lds_dwordx4 v[236:237], off
	s_waitcnt vmcnt(8)
	s_waitcnt lgkmcnt(0)
	s_barrier
	s_setprio 1
	s_waitcnt lgkmcnt(0)
	v_mfma_f32_16x16x32_bf16 v[124:127], v[168:171], v[204:207], v[124:127]
	v_mfma_f32_16x16x32_bf16 v[120:123], v[176:179], v[204:207], v[120:123]
	v_mfma_f32_16x16x32_bf16 v[108:111], v[168:171], v[212:215], v[108:111]
	v_mfma_f32_16x16x32_bf16 v[104:107], v[176:179], v[212:215], v[104:107]
	v_mfma_f32_16x16x32_bf16 v[92:95], v[168:171], v[220:223], v[92:95]
	v_mfma_f32_16x16x32_bf16 v[88:91], v[176:179], v[220:223], v[88:91]
	v_mfma_f32_16x16x32_bf16 v[76:79], v[168:171], v[228:231], v[76:79]
	v_mfma_f32_16x16x32_bf16 v[72:75], v[176:179], v[228:231], v[72:75]
	v_mfma_f32_16x16x32_bf16 v[124:127], v[172:175], v[208:211], v[124:127]
	v_mfma_f32_16x16x32_bf16 v[120:123], v[180:183], v[208:211], v[120:123]
	v_mfma_f32_16x16x32_bf16 v[108:111], v[172:175], v[216:219], v[108:111]
	v_mfma_f32_16x16x32_bf16 v[104:107], v[180:183], v[216:219], v[104:107]
	v_mfma_f32_16x16x32_bf16 v[92:95], v[172:175], v[224:227], v[92:95]
	v_mfma_f32_16x16x32_bf16 v[88:91], v[180:183], v[224:227], v[88:91]
	v_mfma_f32_16x16x32_bf16 v[76:79], v[172:175], v[244:247], v[76:79]
	v_mfma_f32_16x16x32_bf16 v[72:75], v[180:183], v[244:247], v[72:75]
	s_setprio 0
	s_setprio 1
	v_mfma_f32_16x16x32_bf16 v[116:119], v[184:187], v[204:207], v[116:119]
	v_mfma_f32_16x16x32_bf16 v[112:115], v[192:195], v[204:207], v[112:115]
	v_mfma_f32_16x16x32_bf16 v[100:103], v[184:187], v[212:215], v[100:103]
	v_mfma_f32_16x16x32_bf16 v[96:99], v[192:195], v[212:215], v[96:99]
	v_mfma_f32_16x16x32_bf16 v[84:87], v[184:187], v[220:223], v[84:87]
	v_mfma_f32_16x16x32_bf16 v[80:83], v[192:195], v[220:223], v[80:83]
	v_mfma_f32_16x16x32_bf16 v[68:71], v[184:187], v[228:231], v[68:71]
	v_mfma_f32_16x16x32_bf16 v[64:67], v[192:195], v[228:231], v[64:67]
	v_mfma_f32_16x16x32_bf16 v[116:119], v[188:191], v[208:211], v[116:119]
	v_mfma_f32_16x16x32_bf16 v[112:115], v[196:199], v[208:211], v[112:115]
	v_mfma_f32_16x16x32_bf16 v[100:103], v[188:191], v[216:219], v[100:103]
	v_mfma_f32_16x16x32_bf16 v[96:99], v[196:199], v[216:219], v[96:99]
	v_mfma_f32_16x16x32_bf16 v[84:87], v[188:191], v[224:227], v[84:87]
	v_mfma_f32_16x16x32_bf16 v[80:83], v[196:199], v[224:227], v[80:83]
	v_mfma_f32_16x16x32_bf16 v[68:71], v[188:191], v[244:247], v[68:71]
	v_mfma_f32_16x16x32_bf16 v[64:67], v[196:199], v[244:247], v[64:67]
	s_setprio 0
	s_barrier
; #define PG8_STAGE(bufoff, gbase, voff) do { _Pragma("unroll") for (int _i = 0; _i < 2; ++_i) \
;         __builtin_amdgcn_global_load_lds((const unsigned*)((const char*)(gbase) + (voff)[_i]), (LAS unsigned*)(lds + (bufoff) + ldsw + _i * 8192), 16, 0, 0); } while (0)
; #define PG8_LDA(dst, b, h) do { _Pragma("unroll") for (int m = 0; m < 4; ++m) _Pragma("unroll") for (int k = 0; k < 2; ++k) dst[m][k] = *(const LAS bf16x8*)(lds + PG8_SA(b, h) + aoff + m * 2048 + k * 1024); } while (0)
; #define PG8_MMA(ai, bj, At, Bt) do { __builtin_amdgcn_s_setprio(1); _Pragma("unroll") for (int m = 0; m < 4; ++m) _Pragma("unroll") for (int n = 0; n < 2; ++n) _Pragma("unroll") for (int k = 0; k < 2; ++k) \
;         acc[ai][bj][m][n] = __builtin_amdgcn_mfma_f32_16x16x32_bf16(Bt[n][k], At[m][k], acc[ai][bj][m][n], 0, 0, 0); __builtin_amdgcn_s_setprio(0); } while (0)
; #define PG8_WAIT_V(n) asm volatile("s_waitcnt vmcnt(" #n ")" ::: "memory")
; #define PG8_WAIT_L(n) asm volatile("s_waitcnt lgkmcnt(" #n ")" ::: "memory")
; #define PG8_BAR __builtin_amdgcn_s_barrier()
; template <class Epi, class Sched, bool APERM = false, bool HALFN = false>
; __device__ __forceinline__ void gemm_phase(LAS unsigned char* lds, const int tid_in, const int K, const Sched& S, const Epi& E) {
;     ...
;             PG8_LDA(At, 1, 1); PG8_STAGE(PG8_SB(1, 0), b3, voffB); PG8_STAGE(PG8_SB(1, 1), b3 + hstep, voffB); PG8_STAGE(PG8_SA(1, 0), a3, voffA);
;             PG8_WAIT_V(8); PG8_WAIT_L(0); PG8_BAR; PG8_MMA(1, 0, At, B0); if constexpr (!HALFN) PG8_MMA(1, 1, At, B1); PG8_BAR; PG8_SCHED;
;         }
;         if (wr == 0) PG8_BAR;
;         { const Unit fu = S.full(ui); E(acc, fu, wr, wc, fr, fq); }
;     __device__ __forceinline__ GU full(int i) const {
;         GU u; int Lx = i * G + c; const u64* ssq = (const u64*)(ws + WS_SSQ) + (3 * l) * T_;
;         if (Lx < 448) { int pm, pn; tile_order(Lx, 32, 14, pm, pn);
;             u.out = (bf16_t*)(ws + WS_PROJ) + (size_t)pm * 256 * NP + pn * 256; u.sc = ssq + pm * 256;
;             u.gates = (pn == 13) ? (float*)(ws + WS_GATES) + (size_t)pm * 256 * 32 : nullptr; u.ldc = NP; u.mode = 1; return u; }
;         Lx -= 448;
;         if (Lx < 160) { const int pm = Lx % 5, pn = Lx / 5;
;             u.out = (bf16_t*)(ws + WS_VT) + (size_t)pm * 256 * T_ + pn * 256; u.sc = ssq + pn * 256; u.gates = nullptr; u.ldc = T_; u.mode = 2; return u; }
	s_add_i32 s16, s44, s35
	v_lshl_add_u64 v[232:233], v[232:233], 0, s[78:79]
	s_mov_b32 m0, s16
	ds_read_b128 v[204:207], v141 offset:49152
	ds_read_b128 v[208:211], v141 offset:50176
	ds_read_b128 v[212:215], v141 offset:51200
	ds_read_b128 v[216:219], v141 offset:52224
	ds_read_b128 v[220:223], v141 offset:53248
	ds_read_b128 v[224:227], v141 offset:54272
	ds_read_b128 v[228:231], v141 offset:55296
	ds_read_b128 v[244:247], v141 offset:56320
	global_load_lds_dwordx4 v[232:233], off
	s_add_i32 m0, s16, 0x2000
	s_add_u32 s4, s4, 0x80080
	v_lshl_add_u64 v[232:233], v[248:249], 0, s[78:79]
	s_addc_u32 s5, s5, 0
	s_add_i32 s16, s45, s35
	global_load_lds_dwordx4 v[232:233], off
	v_lshl_add_u64 v[232:233], s[4:5], 0, v[130:131]
	s_mov_b32 m0, s16
	s_nop 0
	global_load_lds_dwordx4 v[232:233], off
	v_lshl_add_u64 v[232:233], s[4:5], 0, v[134:135]
	s_add_i32 m0, s16, 0x2000
	s_nop 0
	global_load_lds_dwordx4 v[232:233], off
	v_lshl_add_u64 v[232:233], v[250:251], 0, s[78:79]
	s_mov_b32 m0, s71
	s_nop 0
	global_load_lds_dwordx4 v[232:233], off
	v_lshl_add_u64 v[232:233], v[252:253], 0, s[78:79]
	s_mov_b32 m0, s74
	s_nop 0
	global_load_lds_dwordx4 v[232:233], off
	s_waitcnt vmcnt(8)
	s_waitcnt lgkmcnt(0)
	s_barrier
	s_setprio 1
	s_waitcnt lgkmcnt(0)
	v_mfma_f32_16x16x32_bf16 v[60:63], v[168:171], v[204:207], v[60:63]
	v_mfma_f32_16x16x32_bf16 v[56:59], v[176:179], v[204:207], v[56:59]
	v_mfma_f32_16x16x32_bf16 v[44:47], v[168:171], v[212:215], v[44:47]
	v_mfma_f32_16x16x32_bf16 v[40:43], v[176:179], v[212:215], v[40:43]
	v_mfma_f32_16x16x32_bf16 v[28:31], v[168:171], v[220:223], v[28:31]
	v_mfma_f32_16x16x32_bf16 v[24:27], v[176:179], v[220:223], v[24:27]
	v_mfma_f32_16x16x32_bf16 v[12:15], v[168:171], v[228:231], v[12:15]
	v_mfma_f32_16x16x32_bf16 v[8:11], v[176:179], v[228:231], v[8:11]
	v_mfma_f32_16x16x32_bf16 v[60:63], v[172:175], v[208:211], v[60:63]
	v_mfma_f32_16x16x32_bf16 v[56:59], v[180:183], v[208:211], v[56:59]
	v_mfma_f32_16x16x32_bf16 v[44:47], v[172:175], v[216:219], v[44:47]
	v_mfma_f32_16x16x32_bf16 v[40:43], v[180:183], v[216:219], v[40:43]
	v_mfma_f32_16x16x32_bf16 v[28:31], v[172:175], v[224:227], v[28:31]
	v_mfma_f32_16x16x32_bf16 v[24:27], v[180:183], v[224:227], v[24:27]
	v_mfma_f32_16x16x32_bf16 v[12:15], v[172:175], v[244:247], v[12:15]
	v_mfma_f32_16x16x32_bf16 v[8:11], v[180:183], v[244:247], v[8:11]
	s_setprio 0
	s_setprio 1
	v_mfma_f32_16x16x32_bf16 v[52:55], v[184:187], v[204:207], v[52:55]
	v_mfma_f32_16x16x32_bf16 v[48:51], v[192:195], v[204:207], v[48:51]
	v_mfma_f32_16x16x32_bf16 v[36:39], v[184:187], v[212:215], v[36:39]
	v_mfma_f32_16x16x32_bf16 v[32:35], v[192:195], v[212:215], v[32:35]
	v_mfma_f32_16x16x32_bf16 v[20:23], v[184:187], v[220:223], v[20:23]
	v_mfma_f32_16x16x32_bf16 v[16:19], v[192:195], v[220:223], v[16:19]
	v_mfma_f32_16x16x32_bf16 v[4:7], v[184:187], v[228:231], v[4:7]
	v_mfma_f32_16x16x32_bf16 v[0:3], v[192:195], v[228:231], v[0:3]
	v_mfma_f32_16x16x32_bf16 v[52:55], v[188:191], v[208:211], v[52:55]
	v_mfma_f32_16x16x32_bf16 v[48:51], v[196:199], v[208:211], v[48:51]
	v_mfma_f32_16x16x32_bf16 v[36:39], v[188:191], v[216:219], v[36:39]
	v_mfma_f32_16x16x32_bf16 v[32:35], v[196:199], v[216:219], v[32:35]
	v_mfma_f32_16x16x32_bf16 v[20:23], v[188:191], v[224:227], v[20:23]
	v_mfma_f32_16x16x32_bf16 v[16:19], v[196:199], v[224:227], v[16:19]
	v_mfma_f32_16x16x32_bf16 v[4:7], v[188:191], v[244:247], v[4:7]
	v_mfma_f32_16x16x32_bf16 v[0:3], v[196:199], v[244:247], v[0:3]
	s_setprio 0
	s_barrier
	s_add_i32 s25, s25, 2
	s_add_u32 s23, s23, 0x100
	s_addc_u32 s24, s24, 0
	s_add_u32 s0, s0, 0x100
	s_addc_u32 s1, s1, 0
	s_cmp_gt_u32 s25, 29
	s_cbranch_scc0 .LBB0_346
	s_and_b64 vcc, exec, s[6:7]
	s_cbranch_vccz .LBB0_349
	s_barrier
.LBB0_349:
	s_and_b32 s32, s18, 1
	s_lshl_b32 s32, s32, 11
	s_add_i32 s32, s32, 0x20000
	s_mul_i32 s44, s18, s28
	s_add_i32 s44, s44, s27
	s_cmpk_lt_i32 s44, 0x1c0
	s_cselect_b64 s[22:23], -1, 0
	s_cmpk_gt_i32 s44, 0x1bf
	s_mov_b64 s[0:1], -1
	s_cbranch_scc0 .LBB0_358
	s_cmpk_gt_u32 s44, 0x25f
	s_mov_b64 s[4:5], -1
	s_cbranch_scc0 .LBB0_356
	s_add_i32 s0, s44, 0xfffffda0
	s_lshr_b32 s72, s0, 2
	s_and_b32 s20, s44, 3
	s_lshl_b64 s[0:1], s[72:73], 18
	s_cmp_gt_u32 s20, 1
	s_cbranch_scc0 .LBB0_353
	v_readlane_b32 s4, v255, 46
	s_add_u32 s16, s4, s0
	v_readlane_b32 s4, v255, 47
	s_addc_u32 s17, s4, s1
	s_add_i32 s72, s20, -2
	s_lshl_b64 s[4:5], s[72:73], 17
	s_add_u32 s16, s16, s4
	s_addc_u32 s17, s17, s5
	s_mov_b64 s[4:5], 0

; __device__ __forceinline__ float u64f(u64 q) { return (float)(unsigned)(q >> 32) * 4294967296.f + (float)(unsigned)q; }
;     __device__ __forceinline__ void operator()(const f32x4 (&acc)[2][2][4][2], const GU& u, int wr, int wc, int fr, int fq) const {
;     ...
;                 if ((u.mode & 3) == 2) { const u64* q = u.sc + c0 + bj * 128 + 4 * n;
;                     cs[bj][n] = (f32x4){rsqrtf(u64f(q[0]) * SSQ_INV + EPS), rsqrtf(u64f(q[1]) * SSQ_INV + EPS), rsqrtf(u64f(q[2]) * SSQ_INV + EPS), rsqrtf(u64f(q[3]) * SSQ_INV + EPS)}; }
.LBB0_360:
	v_lshlrev_b32_e32 v168, 3, v140
	v_mov_b32_e32 v169, v201
	v_add_u32_e32 v184, s32, v168
	v_cndmask_b32_e64 v169, 0, 1, s[4:5]
	v_mov_b32_e32 v168, 1.0
	v_cmp_ne_u32_e64 s[0:1], 1, v169
	s_andn2_b64 vcc, exec, s[4:5]
	v_mov_b32_e32 v170, 1.0
	v_mov_b32_e32 v171, 1.0
	v_mov_b32_e32 v172, 1.0
	v_mov_b32_e32 v173, 1.0
	s_cbranch_vccnz .LBB0_362
	ds_read_b128 v[170:173], v184
	s_min_u32 s44, s91, 32
	v_mov_b32_e32 v175, v201
	v_mov_b32_e32 v177, v201
	s_sub_i32 s45, 32, s44
	s_mov_b32 s4, 0x358637bd
	v_mov_b32_e32 v179, v201
	v_mov_b32_e32 v181, v201
	s_waitcnt lgkmcnt(0)
	v_mov_b32_e32 v174, v173
	v_lshlrev_b64 v[174:175], s44, v[174:175]
	v_min_u32_e32 v169, 1, v174
	v_or_b32_e32 v169, v175, v169
	v_cvt_f32_u32_e32 v169, v169
	v_mov_b32_e32 v176, v171
	v_lshlrev_b64 v[176:177], s44, v[176:177]
	v_cvt_f32_u32_e32 v171, v172
	v_ldexp_f32 v175, v169, s45
	v_min_u32_e32 v169, 1, v176
	v_or_b32_e32 v169, v177, v169
	v_cvt_f32_u32_e32 v169, v169
	v_cvt_f32_u32_e32 v170, v170
	v_mov_b64_e32 v[172:173], s[4:5]
	v_ldexp_f32 v174, v169, s45
	v_pk_fma_f32 v[170:171], v[174:175], s[82:83], v[170:171] op_sel_hi:[1,0,1]
	s_nop 0
	v_pk_fma_f32 v[170:171], v[170:171], s[84:85], v[172:173] op_sel_hi:[1,0,0]
	s_nop 0
	v_mul_f32_e32 v169, 0x4b800000, v170
	v_cmp_gt_f32_e64 s[4:5], s85, v170
	v_cmp_gt_f32_e32 vcc, s85, v171
	s_nop 0
	v_cndmask_b32_e64 v169, v170, v169, s[4:5]
	v_rsq_f32_e32 v170, v169
	v_mul_f32_e32 v169, 0x4b800000, v171
	v_cndmask_b32_e32 v169, v171, v169, vcc
	v_rsq_f32_e32 v171, v169
	s_nop 0
	v_pk_mul_f32 v[174:175], v[170:171], s[88:89] op_sel_hi:[1,0]
	s_nop 0
	v_cndmask_b32_e64 v170, v170, v174, s[4:5]
	v_cndmask_b32_e32 v171, v171, v175, vcc
	ds_read_b128 v[174:177], v184 offset:16
	s_waitcnt lgkmcnt(0)
	v_mov_b32_e32 v178, v177
	v_lshlrev_b64 v[178:179], s44, v[178:179]
	v_min_u32_e32 v169, 1, v178
	v_or_b32_e32 v169, v179, v169
	v_cvt_f32_u32_e32 v169, v169
	v_mov_b32_e32 v180, v175
	v_lshlrev_b64 v[180:181], s44, v[180:181]
	v_cvt_f32_u32_e32 v175, v176
	v_ldexp_f32 v179, v169, s45
	v_min_u32_e32 v169, 1, v180
	v_or_b32_e32 v169, v181, v169
	v_cvt_f32_u32_e32 v169, v169
	v_cvt_f32_u32_e32 v174, v174
	v_ldexp_f32 v178, v169, s45
	v_pk_fma_f32 v[174:175], v[178:179], s[82:83], v[174:175] op_sel_hi:[1,0,1]
	s_nop 0
	v_pk_fma_f32 v[172:173], v[174:175], s[84:85], v[172:173] op_sel_hi:[1,0,0]
	s_nop 0
	v_mul_f32_e32 v169, 0x4b800000, v172
	v_cmp_gt_f32_e64 s[4:5], s85, v172
	v_cmp_gt_f32_e32 vcc, s85, v173
	s_nop 0
	v_cndmask_b32_e64 v169, v172, v169, s[4:5]
	v_rsq_f32_e32 v172, v169
	v_mul_f32_e32 v169, 0x4b800000, v173
	v_cndmask_b32_e32 v169, v173, v169, vcc
	v_rsq_f32_e32 v173, v169
	s_nop 0
	v_pk_mul_f32 v[174:175], v[172:173], s[88:89] op_sel_hi:[1,0]
	s_nop 0
	v_cndmask_b32_e64 v172, v172, v174, s[4:5]
	v_cndmask_b32_e32 v173, v173, v175, vcc
.LBB0_362:
	s_and_b64 vcc, exec, s[0:1]
	v_mov_b32_e32 v169, 1.0
	v_mov_b32_e32 v176, 1.0
	v_mov_b32_e32 v177, 1.0
	s_cbranch_vccnz .LBB0_364
	ds_read_b128 v[174:177], v184 offset:32
	v_mov_b32_e32 v169, v201
	s_min_u32 s44, s91, 32
	v_mov_b32_e32 v179, v201
	s_sub_i32 s45, 32, s44
	s_mov_b32 s4, 0x358637bd
	v_mov_b32_e32 v183, v201
	v_mov_b32_e32 v181, v201
	s_waitcnt lgkmcnt(0)
	v_mov_b32_e32 v168, v177
	v_lshlrev_b64 v[168:169], s44, v[168:169]
	v_min_u32_e32 v168, 1, v168
	v_or_b32_e32 v168, v169, v168
	v_cvt_f32_u32_e32 v168, v168
	v_mov_b32_e32 v178, v175
	v_lshlrev_b64 v[178:179], s44, v[178:179]
	v_cvt_f32_u32_e32 v175, v176
	v_ldexp_f32 v169, v168, s45
	v_min_u32_e32 v168, 1, v178
	v_or_b32_e32 v168, v179, v168
	v_cvt_f32_u32_e32 v168, v168
	v_cvt_f32_u32_e32 v174, v174
	v_ldexp_f32 v168, v168, s45
	v_pk_fma_f32 v[168:169], v[168:169], s[82:83], v[174:175] op_sel_hi:[1,0,1]
	v_mov_b64_e32 v[174:175], s[4:5]
	v_pk_fma_f32 v[168:169], v[168:169], s[84:85], v[174:175] op_sel_hi:[1,0,0]
	s_nop 0
	v_mul_f32_e32 v176, 0x4b800000, v168
	v_cmp_gt_f32_e64 s[4:5], s85, v168
	v_cmp_gt_f32_e32 vcc, s85, v169
	s_nop 0
	v_cndmask_b32_e64 v168, v168, v176, s[4:5]
	v_mul_f32_e32 v176, 0x4b800000, v169
	v_cndmask_b32_e32 v169, v169, v176, vcc
	v_rsq_f32_e32 v168, v168
	v_rsq_f32_e32 v169, v169
	s_nop 0
	v_pk_mul_f32 v[176:177], v[168:169], s[88:89] op_sel_hi:[1,0]
	s_nop 0
	v_cndmask_b32_e64 v168, v168, v176, s[4:5]
	v_cndmask_b32_e32 v169, v169, v177, vcc
	ds_read_b128 v[176:179], v184 offset:48
	s_waitcnt lgkmcnt(0)
	v_mov_b32_e32 v182, v177
	v_lshlrev_b64 v[182:183], s44, v[182:183]
	v_min_u32_e32 v177, 1, v182
	v_mov_b32_e32 v180, v179
	v_or_b32_e32 v177, v183, v177
	v_lshlrev_b64 v[180:181], s44, v[180:181]
	v_cvt_f32_u32_e32 v177, v177
	v_min_u32_e32 v179, 1, v180
	v_or_b32_e32 v179, v181, v179
	v_cvt_f32_u32_e32 v179, v179
	v_ldexp_f32 v180, v177, s45
	v_cvt_f32_u32_e32 v177, v178
	v_cvt_f32_u32_e32 v176, v176
	v_ldexp_f32 v181, v179, s45
	v_pk_fma_f32 v[176:177], v[180:181], s[82:83], v[176:177] op_sel_hi:[1,0,1]
	s_nop 0
	v_pk_fma_f32 v[174:175], v[176:177], s[84:85], v[174:175] op_sel_hi:[1,0,0]
	s_nop 0
	v_mul_f32_e32 v176, 0x4b800000, v174
	v_cmp_gt_f32_e64 s[4:5], s85, v174
	v_cmp_gt_f32_e32 vcc, s85, v175
	s_nop 0
	v_cndmask_b32_e64 v174, v174, v176, s[4:5]
	v_mul_f32_e32 v176, 0x4b800000, v175
	v_cndmask_b32_e32 v175, v175, v176, vcc
	v_rsq_f32_e32 v174, v174
	v_rsq_f32_e32 v175, v175
	s_nop 0
	v_pk_mul_f32 v[176:177], v[174:175], s[88:89] op_sel_hi:[1,0]
	s_nop 0
	v_cndmask_b32_e64 v176, v174, v176, s[4:5]
	v_cndmask_b32_e32 v177, v175, v177, vcc
; __device__ __forceinline__ float u64f(u64 q) { return (float)(unsigned)(q >> 32) * 4294967296.f + (float)(unsigned)q; }
;     __device__ __forceinline__ void operator()(const f32x4 (&acc)[2][2][4][2], const GU& u, int wr, int wc, int fr, int fq) const {
;     ...
;                 if ((u.mode & 3) == 2) { const u64* q = u.sc + c0 + bj * 128 + 4 * n;
;                     cs[bj][n] = (f32x4){rsqrtf(u64f(q[0]) * SSQ_INV + EPS), rsqrtf(u64f(q[1]) * SSQ_INV + EPS), rsqrtf(u64f(q[2]) * SSQ_INV + EPS), rsqrtf(u64f(q[3]) * SSQ_INV + EPS)}; }
.LBB0_364:
	v_mov_b32_e32 v174, 1.0
	s_and_b64 vcc, exec, s[0:1]
	v_mov_b32_e32 v178, 1.0
	v_mov_b32_e32 v179, 1.0
	v_mov_b32_e32 v180, 1.0
	v_mov_b32_e32 v181, 1.0
	s_cbranch_vccnz .LBB0_366
	ds_read_b128 v[178:181], v184 offset:1024
	v_mov_b32_e32 v183, v201
	s_min_u32 s44, s91, 32
	v_mov_b32_e32 v187, v201
	s_sub_i32 s45, 32, s44
	s_mov_b32 s4, 0x358637bd
	v_mov_b32_e32 v191, v201
	s_waitcnt lgkmcnt(0)
	v_mov_b32_e32 v182, v181
	v_lshlrev_b64 v[182:183], s44, v[182:183]
	v_min_u32_e32 v175, 1, v182
	v_or_b32_e32 v175, v183, v175
	v_cvt_f32_u32_e32 v175, v175
	v_mov_b32_e32 v186, v179
	v_lshlrev_b64 v[186:187], s44, v[186:187]
	v_cvt_f32_u32_e32 v179, v180
	v_ldexp_f32 v183, v175, s45
	v_min_u32_e32 v175, 1, v186
	v_or_b32_e32 v175, v187, v175
	ds_read_b128 v[186:189], v184 offset:1040
	v_cvt_f32_u32_e32 v175, v175
	v_cvt_f32_u32_e32 v178, v178
	v_mov_b64_e32 v[180:181], s[4:5]
	v_ldexp_f32 v182, v175, s45
	v_pk_fma_f32 v[178:179], v[182:183], s[82:83], v[178:179] op_sel_hi:[1,0,1]
	s_waitcnt lgkmcnt(0)
	v_mov_b32_e32 v190, v187
	v_pk_fma_f32 v[178:179], v[178:179], s[84:85], v[180:181] op_sel_hi:[1,0,0]
	v_lshlrev_b64 v[190:191], s44, v[190:191]
	v_mul_f32_e32 v175, 0x4b800000, v178
	v_cmp_gt_f32_e64 s[4:5], s85, v178
	v_cmp_gt_f32_e32 vcc, s85, v179
	v_cvt_f32_u32_e32 v187, v188
	v_cndmask_b32_e64 v175, v178, v175, s[4:5]
	v_rsq_f32_e32 v178, v175
	v_mul_f32_e32 v175, 0x4b800000, v179
	v_cndmask_b32_e32 v175, v179, v175, vcc
	v_rsq_f32_e32 v179, v175
	v_cvt_f32_u32_e32 v186, v186
	v_pk_mul_f32 v[182:183], v[178:179], s[88:89] op_sel_hi:[1,0]
	s_nop 0
	v_cndmask_b32_e64 v178, v178, v182, s[4:5]
	v_cndmask_b32_e32 v179, v179, v183, vcc
	v_mov_b32_e32 v182, v189
	v_mov_b32_e32 v183, v201
	v_lshlrev_b64 v[182:183], s44, v[182:183]
	v_min_u32_e32 v175, 1, v182
	v_or_b32_e32 v175, v183, v175
	v_cvt_f32_u32_e32 v175, v175
	v_ldexp_f32 v183, v175, s45
	v_min_u32_e32 v175, 1, v190
	v_or_b32_e32 v175, v191, v175
	v_cvt_f32_u32_e32 v175, v175
	v_ldexp_f32 v182, v175, s45
	v_pk_fma_f32 v[182:183], v[182:183], s[82:83], v[186:187] op_sel_hi:[1,0,1]
	s_nop 0
	v_pk_fma_f32 v[180:181], v[182:183], s[84:85], v[180:181] op_sel_hi:[1,0,0]
	s_nop 0
	v_mul_f32_e32 v175, 0x4b800000, v180
	v_cmp_gt_f32_e64 s[4:5], s85, v180
	v_cmp_gt_f32_e32 vcc, s85, v181
	s_nop 0
	v_cndmask_b32_e64 v175, v180, v175, s[4:5]
	v_rsq_f32_e32 v180, v175
	v_mul_f32_e32 v175, 0x4b800000, v181
	v_cndmask_b32_e32 v175, v181, v175, vcc
	v_rsq_f32_e32 v181, v175
	s_nop 0
	v_pk_mul_f32 v[182:183], v[180:181], s[88:89] op_sel_hi:[1,0]
	s_nop 0
	v_cndmask_b32_e64 v180, v180, v182, s[4:5]
	v_cndmask_b32_e32 v181, v181, v183, vcc
.LBB0_366:
	s_and_b64 vcc, exec, s[0:1]
	v_mov_b32_e32 v175, 1.0
	v_mov_b32_e32 v182, 1.0
	v_mov_b32_e32 v183, 1.0
	s_cbranch_vccnz .LBB0_368
	ds_read_b128 v[186:189], v184 offset:1056
	v_mov_b32_e32 v175, v201
	s_min_u32 s4, s91, 32
	v_mov_b32_e32 v183, v201
	s_sub_i32 s5, 32, s4
	s_mov_b32 s0, 0x358637bd
	v_mov_b32_e32 v191, v201
	s_waitcnt lgkmcnt(0)
	v_mov_b32_e32 v174, v189
	v_lshlrev_b64 v[174:175], s4, v[174:175]
	v_min_u32_e32 v174, 1, v174
	v_or_b32_e32 v174, v175, v174
	v_cvt_f32_u32_e32 v174, v174
	v_mov_b32_e32 v182, v187
	v_lshlrev_b64 v[182:183], s4, v[182:183]
	v_mov_b32_e32 v189, v201
	v_ldexp_f32 v175, v174, s5
	v_min_u32_e32 v174, 1, v182
	v_or_b32_e32 v174, v183, v174
	v_cvt_f32_u32_e32 v174, v174
	v_cvt_f32_u32_e32 v183, v188
	v_cvt_f32_u32_e32 v182, v186
	v_ldexp_f32 v174, v174, s5
	v_pk_fma_f32 v[174:175], v[174:175], s[82:83], v[182:183] op_sel_hi:[1,0,1]
	v_mov_b64_e32 v[182:183], s[0:1]
	v_pk_fma_f32 v[174:175], v[174:175], s[84:85], v[182:183] op_sel_hi:[1,0,0]
	s_nop 0
	v_mul_f32_e32 v186, 0x4b800000, v174
	v_cmp_gt_f32_e64 s[0:1], s85, v174
	v_cmp_gt_f32_e32 vcc, s85, v175
	s_nop 0
	v_cndmask_b32_e64 v174, v174, v186, s[0:1]
	v_mul_f32_e32 v186, 0x4b800000, v175
	v_cndmask_b32_e32 v175, v175, v186, vcc
	v_rsq_f32_e32 v174, v174
	v_rsq_f32_e32 v175, v175
	s_nop 0
	v_pk_mul_f32 v[186:187], v[174:175], s[88:89] op_sel_hi:[1,0]
	s_nop 0
	v_cndmask_b32_e64 v174, v174, v186, s[0:1]
	v_cndmask_b32_e32 v175, v175, v187, vcc
	ds_read_b128 v[184:187], v184 offset:1072
	s_waitcnt lgkmcnt(0)
	v_mov_b32_e32 v190, v185
	v_lshlrev_b64 v[190:191], s4, v[190:191]
	v_min_u32_e32 v185, 1, v190
	v_mov_b32_e32 v188, v187
	v_or_b32_e32 v185, v191, v185
	v_lshlrev_b64 v[188:189], s4, v[188:189]
	v_cvt_f32_u32_e32 v185, v185
	v_min_u32_e32 v187, 1, v188
	v_or_b32_e32 v187, v189, v187
	v_cvt_f32_u32_e32 v187, v187
	v_ldexp_f32 v188, v185, s5
	v_cvt_f32_u32_e32 v185, v186
	v_cvt_f32_u32_e32 v184, v184
	v_ldexp_f32 v189, v187, s5
	v_pk_fma_f32 v[184:185], v[188:189], s[82:83], v[184:185] op_sel_hi:[1,0,1]
	s_nop 0
	v_pk_fma_f32 v[182:183], v[184:185], s[84:85], v[182:183] op_sel_hi:[1,0,0]
	s_nop 0
	v_mul_f32_e32 v184, 0x4b800000, v182
	v_cmp_gt_f32_e64 s[0:1], s85, v182
	v_cmp_gt_f32_e32 vcc, s85, v183
	s_nop 0
	v_cndmask_b32_e64 v182, v182, v184, s[0:1]
	v_mul_f32_e32 v184, 0x4b800000, v183
	v_cndmask_b32_e32 v183, v183, v184, vcc
	v_rsq_f32_e32 v182, v182
	v_rsq_f32_e32 v183, v183
	s_nop 0
	v_pk_mul_f32 v[184:185], v[182:183], s[88:89] op_sel_hi:[1,0]
	s_nop 0
	v_cndmask_b32_e64 v182, v182, v184, s[0:1]
	v_cndmask_b32_e32 v183, v183, v185, vcc
; __device__ __forceinline__ float u64f(u64 q) { return (float)(unsigned)(q >> 32) * 4294967296.f + (float)(unsigned)q; }
;     __device__ __forceinline__ void operator()(const f32x4 (&acc)[2][2][4][2], const GU& u, int wr, int wc, int fr, int fq) const {
;     ...
;         if ((u.mode & 3) == 1) { u64 q_[2][4];
; #pragma unroll
;             for (int ai = 0; ai < 2; ++ai)
; #pragma unroll
;                 for (int m = 0; m < 4; ++m) q_[ai][m] = u.sc[r0 + ai * 128 + m * 16];
; #pragma unroll
;             for (int ai = 0; ai < 2; ++ai)
; #pragma unroll
;                 for (int m = 0; m < 4; ++m) rsv[ai][m] = rsqrtf(u64f(q_[ai][m]) * SSQ_INV + EPS);
.LBB0_368:
	v_mov_b32_e32 v186, 1.0
	s_andn2_b64 vcc, exec, s[22:23]
	v_mov_b32_e32 v187, v186
	v_mov_b32_e32 v188, v186
	v_mov_b32_e32 v189, v186
	v_mov_b32_e32 v184, v186
	v_mov_b32_e32 v185, v186
	v_mov_b32_e32 v190, v186
	v_mov_b32_e32 v191, v186
	s_cbranch_vccnz .LBB0_370
	v_lshl_add_u32 v186, v136, 3, s32
	ds_read_b64 v[188:189], v186
	ds_read_b64 v[194:195], v186 offset:128
	ds_read_b64 v[198:199], v186 offset:256
	ds_read_b64 v[204:205], v186 offset:384
	ds_read_b64 v[184:185], v186 offset:1024
	ds_read_b64 v[196:197], v186 offset:1152
	ds_read_b64 v[190:191], v186 offset:1280
	ds_read_b64 v[192:193], v186 offset:1408
	v_mov_b32_e32 v187, v201
	s_min_u32 s4, s91, 32
	v_mov_b32_e32 v207, v201
	s_sub_i32 s5, 32, s4
	s_mov_b32 s0, 0x358637bd
	s_waitcnt lgkmcnt(0)
	v_mov_b32_e32 v206, v189
	v_mov_b32_e32 v186, v195
	v_lshlrev_b64 v[186:187], s4, v[186:187]
	v_min_u32_e32 v186, 1, v186
	v_or_b32_e32 v186, v187, v186
	v_cvt_f32_u32_e32 v186, v186
	v_lshlrev_b64 v[206:207], s4, v[206:207]
	v_cvt_f32_u32_e32 v189, v194
	v_cvt_f32_u32_e32 v188, v188
	v_ldexp_f32 v187, v186, s5
	v_min_u32_e32 v186, 1, v206
	v_or_b32_e32 v186, v207, v186
	v_cvt_f32_u32_e32 v186, v186
	v_mov_b64_e32 v[194:195], s[0:1]
	v_mov_b32_e32 v206, v199
	v_mov_b32_e32 v207, v201
	v_ldexp_f32 v186, v186, s5
	v_pk_fma_f32 v[186:187], v[186:187], s[82:83], v[188:189] op_sel_hi:[1,0,1]
	v_lshlrev_b64 v[206:207], s4, v[206:207]
	v_pk_fma_f32 v[186:187], v[186:187], s[84:85], v[194:195] op_sel_hi:[1,0,0]
	v_cvt_f32_u32_e32 v199, v204
	v_mul_f32_e32 v188, 0x4b800000, v186
	v_cmp_gt_f32_e64 s[0:1], s85, v186
	v_cmp_gt_f32_e32 vcc, s85, v187
	v_cvt_f32_u32_e32 v198, v198
	v_cndmask_b32_e64 v186, v186, v188, s[0:1]
	v_mul_f32_e32 v188, 0x4b800000, v187
	v_cndmask_b32_e32 v187, v187, v188, vcc
	v_rsq_f32_e32 v186, v186
	v_rsq_f32_e32 v187, v187
	v_mov_b32_e32 v204, v185
	v_cvt_f32_u32_e32 v184, v184
	v_cvt_f32_u32_e32 v190, v190
	v_pk_mul_f32 v[188:189], v[186:187], s[88:89] op_sel_hi:[1,0]
	s_nop 0
	v_cndmask_b32_e64 v188, v186, v188, s[0:1]
	v_cndmask_b32_e32 v189, v187, v189, vcc
	v_mov_b32_e32 v186, v205
	v_mov_b32_e32 v187, v201
	v_lshlrev_b64 v[186:187], s4, v[186:187]
	v_min_u32_e32 v186, 1, v186
	v_or_b32_e32 v186, v187, v186
	v_cvt_f32_u32_e32 v186, v186
	v_mov_b32_e32 v205, v201
	v_lshlrev_b64 v[204:205], s4, v[204:205]
	v_min_u32_e32 v185, 1, v204
	v_ldexp_f32 v187, v186, s5
	v_min_u32_e32 v186, 1, v206
	v_or_b32_e32 v186, v207, v186
	v_cvt_f32_u32_e32 v186, v186
	v_or_b32_e32 v185, v205, v185
	v_cvt_f32_u32_e32 v185, v185
	v_ldexp_f32 v186, v186, s5
	v_pk_fma_f32 v[186:187], v[186:187], s[82:83], v[198:199] op_sel_hi:[1,0,1]
	s_nop 0
	v_pk_fma_f32 v[186:187], v[186:187], s[84:85], v[194:195] op_sel_hi:[1,0,0]
	s_nop 0
	v_mul_f32_e32 v198, 0x4b800000, v186
	v_cmp_gt_f32_e64 s[0:1], s85, v186
	v_cmp_gt_f32_e32 vcc, s85, v187
	s_nop 0
	v_cndmask_b32_e64 v186, v186, v198, s[0:1]
	v_mul_f32_e32 v198, 0x4b800000, v187
	v_cndmask_b32_e32 v187, v187, v198, vcc
	v_rsq_f32_e32 v186, v186
	v_rsq_f32_e32 v187, v187
	s_nop 0
	v_pk_mul_f32 v[198:199], v[186:187], s[88:89] op_sel_hi:[1,0]
	s_nop 0
	v_cndmask_b32_e64 v186, v186, v198, s[0:1]
	v_cndmask_b32_e32 v187, v187, v199, vcc
	v_mov_b32_e32 v198, v197
	v_mov_b32_e32 v199, v201
	v_lshlrev_b64 v[198:199], s4, v[198:199]
	v_min_u32_e32 v197, 1, v198
	v_or_b32_e32 v197, v199, v197
	v_cvt_f32_u32_e32 v197, v197
	v_ldexp_f32 v198, v185, s5
	v_cvt_f32_u32_e32 v185, v196
	v_ldexp_f32 v199, v197, s5
	v_pk_fma_f32 v[184:185], v[198:199], s[82:83], v[184:185] op_sel_hi:[1,0,1]
	s_nop 0
	v_pk_fma_f32 v[184:185], v[184:185], s[84:85], v[194:195] op_sel_hi:[1,0,0]
	v_mov_b32_e32 v198, v191
	v_mul_f32_e32 v196, 0x4b800000, v184
	v_cmp_gt_f32_e64 s[0:1], s85, v184
	v_cmp_gt_f32_e32 vcc, s85, v185
	v_mov_b32_e32 v199, v201
	v_cndmask_b32_e64 v184, v184, v196, s[0:1]
	v_mul_f32_e32 v196, 0x4b800000, v185
	v_cndmask_b32_e32 v185, v185, v196, vcc
	v_rsq_f32_e32 v184, v184
	v_rsq_f32_e32 v185, v185
	v_lshlrev_b64 v[198:199], s4, v[198:199]
	v_min_u32_e32 v191, 1, v198
	v_or_b32_e32 v191, v199, v191
	v_pk_mul_f32 v[196:197], v[184:185], s[88:89] op_sel_hi:[1,0]
	v_cvt_f32_u32_e32 v191, v191
	v_cndmask_b32_e64 v184, v184, v196, s[0:1]
	v_cndmask_b32_e32 v185, v185, v197, vcc
	v_mov_b32_e32 v196, v193
	v_mov_b32_e32 v197, v201
	v_lshlrev_b64 v[196:197], s4, v[196:197]
	v_min_u32_e32 v193, 1, v196
	v_or_b32_e32 v193, v197, v193
	v_cvt_f32_u32_e32 v193, v193
	v_ldexp_f32 v196, v191, s5
	v_cvt_f32_u32_e32 v191, v192
	v_ldexp_f32 v197, v193, s5
	v_pk_fma_f32 v[190:191], v[196:197], s[82:83], v[190:191] op_sel_hi:[1,0,1]
	s_nop 0
	v_pk_fma_f32 v[190:191], v[190:191], s[84:85], v[194:195] op_sel_hi:[1,0,0]
	s_nop 0
	v_mul_f32_e32 v192, 0x4b800000, v190
	v_cmp_gt_f32_e64 s[0:1], s85, v190
	v_cmp_gt_f32_e32 vcc, s85, v191
	s_nop 0
	v_cndmask_b32_e64 v190, v190, v192, s[0:1]
	v_mul_f32_e32 v192, 0x4b800000, v191
	v_cndmask_b32_e32 v191, v191, v192, vcc
	v_rsq_f32_e32 v190, v190
	v_rsq_f32_e32 v191, v191
	s_nop 0
	v_pk_mul_f32 v[192:193], v[190:191], s[88:89] op_sel_hi:[1,0]
	s_nop 0
	v_cndmask_b32_e64 v190, v190, v192, s[0:1]
	v_cndmask_b32_e32 v191, v191, v193, vcc
